# layer-0 w_in GEMM: one tile group per XCD with 6 positions of stagger and the 96 context-row tiles as the split round (one row tile x 12 column tiles per XCD)
# baseline (speedup 1.0000x reference)
.Lgi_sk_rm0:
	s_and_b32 s0, s57, 7
	s_lshr_b32 s1, s57, 3
	s_mul_i32 s57, s0, 6
	s_add_u32 s1, s1, s57
	s_cmpk_ge_u32 s1, 192
	s_cselect_b32 s57, 192, 0
	s_sub_u32 s1, s1, s57
	s_mul_i32 s0, s0, 192
	s_add_u32 s57, s0, s1
	s_branch .Lgi_sk_inv
